# v16 + XCD-local norm rows + DFT table rows 0..S/2 only + AT work list without empty items
# speedup vs baseline: 1.0030x; 1.0030x over previous
.LBB0_562:
	s_or_b64 exec, exec, s[0:1]
	v_mov_b32_e32 v0, s11
	s_waitcnt lgkmcnt(0)
	s_barrier
	ds_read_b32 v0, v0
	s_movk_i32 s0, 0x497
	s_waitcnt lgkmcnt(0)
	v_cmp_lt_i32_e32 vcc, s0, v0
	v_readfirstlane_b32 s77, v0
	s_mov_b64 s[0:1], -1
	s_cbranch_vccnz .LBB0_559
	s_cmpk_lt_u32 s77, 0x200
	s_cbranch_scc1 .Lq_d
	s_cmpk_ge_u32 s77, 0x240
	s_cbranch_scc1 .Lq_2
	s_sub_i32 s34, s77, 0x200
	s_lshr_b32 s35, s34, 4
	s_lshl_b32 s35, s35, 5
	s_and_b32 s34, s34, 15
	s_add_i32 s34, s34, s35
	s_add_i32 s77, s34, 0x200
	s_branch .Lq_d

.Lq_3:
	s_cmpk_ge_u32 s77, 0x448
	s_cbranch_scc1 .Lq_4
	s_add_i32 s77, s77, 56
	s_branch .Lq_d
.Lq_4:
	s_cmpk_ge_u32 s77, 0x488
	s_cbranch_scc1 .Lq_5
	s_sub_i32 s34, s77, 0x448
	s_lshr_b32 s35, s34, 3
	s_lshl_b32 s35, s35, 4
	s_and_b32 s34, s34, 7
	s_add_i32 s34, s34, s35
	s_add_i32 s77, s34, 0x480
	s_branch .Lq_d
